# P6a head loop: weight-staging waits count the 26 younger operations (no full store drain per head); two redundant vmcnt(3) dropped
# baseline (speedup 1.0000x reference)
; __device__ __forceinline__ void prep_rwkv_phase(const Params& p, LAS unsigned char* lds, int gw, int ngw, int wave, int lane) {
;     ...
;     for (int h = 0; h < 8; ++h) {
;         if (h < 7) prep_w_load(p, h + 1, tid, wreg);
.LBB0_855:
	s_cmpk_lg_i32 s31, 0x700
	s_cselect_b64 s[22:23], -1, 0
	s_cmpk_eq_i32 s31, 0x700
	s_cbranch_scc1 .LBB0_857
	v_lshl_add_u64 v[0:1], s[92:93], 0, v[146:147]
	s_nop 0
	v_add_co_u32_e32 v4, vcc, 0x2a82000, v0
	s_nop 1
	v_addc_co_u32_e32 v5, vcc, 0, v1, vcc
	v_add_co_u32_e32 v0, vcc, 0x2a92000, v0
	s_nop 1
	v_addc_co_u32_e32 v1, vcc, 0, v1, vcc
	global_load_dwordx4 v[4:7], v[4:5], off
	s_nop 0
	global_load_dwordx4 v[8:11], v[0:1], off
	v_lshl_add_u64 v[0:1], s[92:93], 0, v[148:149]
	s_nop 0
	v_add_co_u32_e32 v12, vcc, 0x2aa4000, v0
	s_nop 1
	v_addc_co_u32_e32 v13, vcc, 0, v1, vcc
	v_add_co_u32_e32 v0, vcc, 0x2aa6000, v0
	s_nop 1
	v_addc_co_u32_e32 v1, vcc, 0, v1, vcc
	global_load_dwordx4 v[12:15], v[12:13], off
	s_nop 0
	global_load_dwordx4 v[16:19], v[0:1], off

; #define BAR_LDS() do { asm volatile("s_waitcnt lgkmcnt(0)" ::: "memory"); __builtin_amdgcn_s_barrier(); asm volatile("" ::: "memory"); } while (0)
; __device__ __forceinline__ void prep_rwkv_phase(const Params& p, LAS unsigned char* lds, int gw, int ngw, int wave, int lane) {
;     ...
;         BAR_LDS();
;         if (h < 7) { prep_w_store(lds, tid, wreg); BAR_LDS(); }
.LBB0_861:
	s_waitcnt lgkmcnt(0)
	s_barrier
	s_andn2_b64 vcc, exec, s[22:23]
	s_cbranch_vccnz .LBB0_854
	s_andn2_b64 vcc, exec, s[20:21]
	s_cbranch_vccnz .Lp6w_inact
	s_waitcnt vmcnt(29)
	ds_write_b128 v209, v[4:7]
	s_waitcnt vmcnt(28)
	ds_write_b128 v210, v[8:11]
	s_waitcnt vmcnt(27)
	ds_write_b128 v211, v[12:15]
	s_waitcnt vmcnt(26)
	ds_write_b128 v211, v[16:19] offset:8704
	s_branch .Lp6w_join
.Lp6w_inact:
	s_waitcnt vmcnt(3)
	ds_write_b128 v209, v[4:7]
	s_waitcnt vmcnt(2)
	ds_write_b128 v210, v[8:11]
	s_waitcnt vmcnt(1)
	ds_write_b128 v211, v[12:15]
	s_waitcnt vmcnt(0)
	ds_write_b128 v211, v[16:19] offset:8704
.Lp6w_join:
	s_waitcnt lgkmcnt(0)
	s_barrier
	s_branch .LBB0_854
